# indexer sweeps: query fragments of heads 0-3 resident in VGPRs (8 fewer ds_read_b128 per iteration), later code kept at the same byte offsets
# speedup vs baseline: 1.0068x; 1.0068x over previous
;     ...
;     const int kt0 = wid >> 1; const int nit = kt0 <= c ? 2 * ((c - kt0) / 4 + 1) : 0;
;     const float t_lo = bucket_lo((int)pref), t_hi = bucket_lo((int)pref + 1);
;     const bf16_t* ikp = Zb + (size_t)(64 * kt0 + r32) * NZ + ZIK + hi * 8;
;     bf16x8 a0, a1;
;     if (nit > 0) { a0 = *(const bf16x8*)ikp; a1 = *(const bf16x8*)(ikp + 16); }
; #pragma unroll 1
;     for (int it = 0; it < nit; ++it) {
;         const int kt = kt0 + 4 * (it >> 1), kb = it & 1;
;         const int itn = it + 1 < nit ? it + 1 : it;
;         const bf16_t* np = ikp + (size_t)(256 * (itn >> 1) + 32 * (itn & 1)) * NZ; const bf16x8 n0 = *(const bf16x8*)np, n1 = *(const bf16x8*)(np + 16);
;         f32x2v sc2[8];
; #pragma unroll
;         for (int r = 0; r < 8; ++r) sc2[r] = (f32x2v){0.f, 0.f};
;     ...
;         { f32x16 zero16;
; #pragma unroll
;           for (int r = 0; r < 16; ++r) zero16[r] = 0.f;
;           f32x16 dA0, dA1, dB0, dB1; float wA0, wA1, wB0, wB1;
;           SW_MF(0, dA0, dA1, wA0, wA1);
;           SW_MF(1, dB0, dB1, wB0, wB1); __builtin_amdgcn_sched_barrier(0);
;           SW_VA(dA0, dA1, wA0, wA1);    __builtin_amdgcn_sched_barrier(0);
;           SW_MF(2, dA0, dA1, wA0, wA1); __builtin_amdgcn_sched_barrier(0);
;           SW_VA(dB0, dB1, wB0, wB1);    __builtin_amdgcn_sched_barrier(0);
;           SW_MF(3, dB0, dB1, wB0, wB1); __builtin_amdgcn_sched_barrier(0);
;           SW_VA(dA0, dA1, wA0, wA1);    __builtin_amdgcn_sched_barrier(0);
;           SW_VA(dB0, dB1, wB0, wB1); }
.LBB0_979:
	v_add_u32_e32 v1, 0x200, v1
	v_cmp_lt_u32_e32 vcc, s62, v1
	ds_write_b32 v0, v155
	s_or_b64 s[0:1], vcc, s[0:1]
	v_add_u32_e32 v0, 0x800, v0
	s_andn2_b64 exec, exec, s[0:1]
	s_cbranch_execnz .LBB0_979
	s_or_b64 exec, exec, s[0:1]
	s_lshr_b32 s24, s3, 7
	v_mov_b32_e32 v0, s24
	v_sub_co_u32_e64 v0, s[18:19], s2, v0
	s_lshl_b32 s0, s69, 5
	v_readfirstlane_b32 s1, v0
	v_lshl_or_b32 v2, s24, 6, v151
	v_mov_b64_e32 v[0:1], s[36:37]
	v_and_or_b32 v169, s0, 32, v151
	s_lshr_b32 s1, s1, 1
	v_mad_u64_u32 v[0:1], s[2:3], v2, s61, v[0:1]
	v_lshlrev_b32_e32 v154, 1, v152
	v_lshlrev_b32_e32 v171, 2, v169
	s_and_b32 s25, s1, 0x7ffffffe
	v_lshl_add_u64 v[0:1], v[0:1], 0, v[154:155]
	s_mov_b64 s[2:3], 0x1300
	v_add_u32_e32 v230, 0x100, v171
	v_mad_u32_u24 v165, v169, s86, v199
	v_add_u32_e32 v167, s51, v171
	s_add_i32 s25, s25, 2
	v_lshl_add_u64 v[140:141], v[0:1], 0, s[2:3]
	s_and_b64 vcc, exec, s[18:19]
	s_waitcnt lgkmcnt(0)
	s_barrier
	s_cbranch_vccnz .LBB0_983
	global_load_dwordx4 v[76:79], v[140:141], off
	global_load_dwordx4 v[72:75], v[140:141], off offset:32
	s_mov_b32 s2, 0
	v_mov_b32_e32 v117, 0x280
	v_mov_b32_e32 v118, 0x2ff
	v_add_u32_e32 v116, 0xfffe0000, v230
	v_mov_b32_e32 v112, 0x2c800000
	v_mov_b32_e32 v113, 0x2c800000
	ds_read2st64_b32 v[80:81], v167 offset1:1
	ds_read2st64_b32 v[82:83], v167 offset0:2 offset1:3
	ds_read2st64_b32 v[84:85], v167 offset0:4 offset1:5
	ds_read2st64_b32 v[86:87], v167 offset0:6 offset1:7
	ds_read_b128 v[56:59], v165
	ds_read_b128 v[60:63], v165 offset:32
	ds_read_b128 v[172:175], v165 offset:64
	ds_read_b128 v[176:179], v165 offset:96
	ds_read_b128 v[180:183], v165 offset:128
	ds_read_b128 v[232:235], v165 offset:160
	ds_read_b128 v[236:239], v165 offset:192
	ds_read_b128 v[136:139], v165 offset:224
	ds_read_b128 v[0:3], v165 offset:256
	ds_read_b128 v[4:7], v165 offset:288
	ds_read_b128 v[8:11], v165 offset:320
	ds_read_b128 v[12:15], v165 offset:352
	s_waitcnt lgkmcnt(12)
	v_mov_b32_e32 v104, v81
	v_mov_b32_e32 v106, v83
	v_mov_b32_e32 v108, v85
	v_mov_b32_e32 v110, v87
	s_waitcnt vmcnt(0) lgkmcnt(0)
	s_cmp_lt_u32 s69, 4
	s_cbranch_scc1 .Lstag_m5
	s_sleep 14
.Lstag_m5:
.Lm5_loop:
	v_mfma_f32_32x32x16_bf16 v[16:31], v[76:79], v[56:59], 0
	v_mfma_f32_32x32x16_bf16 v[16:31], v[72:75], v[60:63], v[16:31]
	v_mfma_f32_32x32x16_bf16 v[32:47], v[76:79], v[172:175], 0
	v_mfma_f32_32x32x16_bf16 v[32:47], v[72:75], v[176:179], v[32:47]
	s_add_i32 s1, s2, 1
	s_cmp_lt_u32 s1, s25
	s_cselect_b32 s3, s1, s2
	s_lshl_b32 vcc_lo, s3, 7
	s_and_b32 vcc_lo, vcc_lo, 0x7fffff00
	s_lshl_b32 s3, s3, 5
	s_and_b32 s3, s3, 32
	s_or_b32 s3, vcc_lo, s3
	v_mad_u64_u32 v[114:115], vcc, s3, v223, v[140:141]
	global_load_dwordx4 v[64:67], v[114:115], off
	global_load_dwordx4 v[68:71], v[114:115], off offset:32
	v_pk_mul_f32 v[16:17], v[16:17], v[112:113] clamp
	v_pk_mul_f32 v[18:19], v[18:19], v[112:113] clamp
	v_pk_mul_f32 v[20:21], v[20:21], v[112:113] clamp
	v_pk_mul_f32 v[22:23], v[22:23], v[112:113] clamp
	v_pk_mul_f32 v[24:25], v[24:25], v[112:113] clamp
	v_pk_mul_f32 v[26:27], v[26:27], v[112:113] clamp
	v_pk_mul_f32 v[28:29], v[28:29], v[112:113] clamp
	v_pk_mul_f32 v[30:31], v[30:31], v[112:113] clamp
	v_pk_fma_f32 v[88:89], v[16:17], v[80:81], 0 op_sel_hi:[1,0,0]
	v_pk_fma_f32 v[90:91], v[18:19], v[80:81], 0 op_sel_hi:[1,0,0]
	v_pk_fma_f32 v[92:93], v[20:21], v[80:81], 0 op_sel_hi:[1,0,0]
	v_pk_fma_f32 v[94:95], v[22:23], v[80:81], 0 op_sel_hi:[1,0,0]
	v_pk_fma_f32 v[96:97], v[24:25], v[80:81], 0 op_sel_hi:[1,0,0]
	v_pk_fma_f32 v[98:99], v[26:27], v[80:81], 0 op_sel_hi:[1,0,0]
	v_pk_fma_f32 v[100:101], v[28:29], v[80:81], 0 op_sel_hi:[1,0,0]
	v_pk_fma_f32 v[102:103], v[30:31], v[80:81], 0 op_sel_hi:[1,0,0]
	v_mfma_f32_32x32x16_bf16 v[16:31], v[76:79], v[180:183], 0
	v_mfma_f32_32x32x16_bf16 v[16:31], v[72:75], v[232:235], v[16:31]
	v_pk_mul_f32 v[32:33], v[32:33], v[112:113] clamp
	v_pk_mul_f32 v[34:35], v[34:35], v[112:113] clamp
	v_pk_mul_f32 v[36:37], v[36:37], v[112:113] clamp
	v_pk_mul_f32 v[38:39], v[38:39], v[112:113] clamp
	v_pk_mul_f32 v[40:41], v[40:41], v[112:113] clamp
	v_pk_mul_f32 v[42:43], v[42:43], v[112:113] clamp
	v_pk_mul_f32 v[44:45], v[44:45], v[112:113] clamp
	v_pk_mul_f32 v[46:47], v[46:47], v[112:113] clamp
	v_pk_fma_f32 v[88:89], v[32:33], v[104:105], v[88:89] op_sel_hi:[1,0,1]
	v_pk_fma_f32 v[90:91], v[34:35], v[104:105], v[90:91] op_sel_hi:[1,0,1]
	v_pk_fma_f32 v[92:93], v[36:37], v[104:105], v[92:93] op_sel_hi:[1,0,1]
	v_pk_fma_f32 v[94:95], v[38:39], v[104:105], v[94:95] op_sel_hi:[1,0,1]
	v_pk_fma_f32 v[96:97], v[40:41], v[104:105], v[96:97] op_sel_hi:[1,0,1]
	v_pk_fma_f32 v[98:99], v[42:43], v[104:105], v[98:99] op_sel_hi:[1,0,1]
	v_pk_fma_f32 v[100:101], v[44:45], v[104:105], v[100:101] op_sel_hi:[1,0,1]
	v_pk_fma_f32 v[102:103], v[46:47], v[104:105], v[102:103] op_sel_hi:[1,0,1]
	v_mfma_f32_32x32x16_bf16 v[32:47], v[76:79], v[236:239], 0
	v_mfma_f32_32x32x16_bf16 v[32:47], v[72:75], v[136:139], v[32:47]
	v_pk_mul_f32 v[16:17], v[16:17], v[112:113] clamp
	v_pk_mul_f32 v[18:19], v[18:19], v[112:113] clamp
	v_pk_mul_f32 v[20:21], v[20:21], v[112:113] clamp
	v_pk_mul_f32 v[22:23], v[22:23], v[112:113] clamp
	v_pk_mul_f32 v[24:25], v[24:25], v[112:113] clamp
	v_pk_mul_f32 v[26:27], v[26:27], v[112:113] clamp
	v_pk_mul_f32 v[28:29], v[28:29], v[112:113] clamp
	v_pk_mul_f32 v[30:31], v[30:31], v[112:113] clamp
	v_pk_fma_f32 v[88:89], v[16:17], v[82:83], v[88:89] op_sel_hi:[1,0,1]
	v_pk_fma_f32 v[90:91], v[18:19], v[82:83], v[90:91] op_sel_hi:[1,0,1]
	v_pk_fma_f32 v[92:93], v[20:21], v[82:83], v[92:93] op_sel_hi:[1,0,1]
	v_pk_fma_f32 v[94:95], v[22:23], v[82:83], v[94:95] op_sel_hi:[1,0,1]
;     ...
;         { f32x16 zero16;
; #pragma unroll
;           for (int r = 0; r < 16; ++r) zero16[r] = 0.f;
;           f32x16 dA0, dA1, dB0, dB1; float wA0, wA1, wB0, wB1;
;           SW_MF(0, dA0, dA1, wA0, wA1);
;           SW_MF(1, dB0, dB1, wB0, wB1); __builtin_amdgcn_sched_barrier(0);
;           SW_VA(dA0, dA1, wA0, wA1);    __builtin_amdgcn_sched_barrier(0);
;           SW_MF(2, dA0, dA1, wA0, wA1); __builtin_amdgcn_sched_barrier(0);
;           SW_VA(dB0, dB1, wB0, wB1);    __builtin_amdgcn_sched_barrier(0);
;           SW_MF(3, dB0, dB1, wB0, wB1); __builtin_amdgcn_sched_barrier(0);
;           SW_VA(dA0, dA1, wA0, wA1);    __builtin_amdgcn_sched_barrier(0);
;           SW_VA(dB0, dB1, wB0, wB1); }
	v_pk_fma_f32 v[96:97], v[24:25], v[82:83], v[96:97] op_sel_hi:[1,0,1]
	v_pk_fma_f32 v[98:99], v[26:27], v[82:83], v[98:99] op_sel_hi:[1,0,1]
	v_pk_fma_f32 v[100:101], v[28:29], v[82:83], v[100:101] op_sel_hi:[1,0,1]
	v_pk_fma_f32 v[102:103], v[30:31], v[82:83], v[102:103] op_sel_hi:[1,0,1]
	v_mfma_f32_32x32x16_bf16 v[16:31], v[76:79], v[0:3], 0
	v_mfma_f32_32x32x16_bf16 v[16:31], v[72:75], v[4:7], v[16:31]
	ds_read_b128 v[0:3], v165 offset:384
	ds_read_b128 v[4:7], v165 offset:416
	v_pk_mul_f32 v[32:33], v[32:33], v[112:113] clamp
	v_pk_mul_f32 v[34:35], v[34:35], v[112:113] clamp
	v_pk_mul_f32 v[36:37], v[36:37], v[112:113] clamp
	v_pk_mul_f32 v[38:39], v[38:39], v[112:113] clamp
	v_pk_mul_f32 v[40:41], v[40:41], v[112:113] clamp
	v_pk_mul_f32 v[42:43], v[42:43], v[112:113] clamp
	v_pk_mul_f32 v[44:45], v[44:45], v[112:113] clamp
	v_pk_mul_f32 v[46:47], v[46:47], v[112:113] clamp
	v_pk_fma_f32 v[88:89], v[32:33], v[106:107], v[88:89] op_sel_hi:[1,0,1]
	v_pk_fma_f32 v[90:91], v[34:35], v[106:107], v[90:91] op_sel_hi:[1,0,1]
	v_pk_fma_f32 v[92:93], v[36:37], v[106:107], v[92:93] op_sel_hi:[1,0,1]
	v_pk_fma_f32 v[94:95], v[38:39], v[106:107], v[94:95] op_sel_hi:[1,0,1]
	v_pk_fma_f32 v[96:97], v[40:41], v[106:107], v[96:97] op_sel_hi:[1,0,1]
	v_pk_fma_f32 v[98:99], v[42:43], v[106:107], v[98:99] op_sel_hi:[1,0,1]
	v_pk_fma_f32 v[100:101], v[44:45], v[106:107], v[100:101] op_sel_hi:[1,0,1]
	v_pk_fma_f32 v[102:103], v[46:47], v[106:107], v[102:103] op_sel_hi:[1,0,1]
	v_mfma_f32_32x32x16_bf16 v[32:47], v[76:79], v[8:11], 0
	v_mfma_f32_32x32x16_bf16 v[32:47], v[72:75], v[12:15], v[32:47]
	ds_read_b128 v[8:11], v165 offset:448
	ds_read_b128 v[12:15], v165 offset:480
	v_pk_mul_f32 v[16:17], v[16:17], v[112:113] clamp
	v_pk_mul_f32 v[18:19], v[18:19], v[112:113] clamp
	v_pk_mul_f32 v[20:21], v[20:21], v[112:113] clamp
	v_pk_mul_f32 v[22:23], v[22:23], v[112:113] clamp
	v_pk_mul_f32 v[24:25], v[24:25], v[112:113] clamp
	v_pk_mul_f32 v[26:27], v[26:27], v[112:113] clamp
	v_pk_mul_f32 v[28:29], v[28:29], v[112:113] clamp
	v_pk_mul_f32 v[30:31], v[30:31], v[112:113] clamp
	v_pk_fma_f32 v[88:89], v[16:17], v[84:85], v[88:89] op_sel_hi:[1,0,1]
	v_pk_fma_f32 v[90:91], v[18:19], v[84:85], v[90:91] op_sel_hi:[1,0,1]
	v_pk_fma_f32 v[92:93], v[20:21], v[84:85], v[92:93] op_sel_hi:[1,0,1]
	v_pk_fma_f32 v[94:95], v[22:23], v[84:85], v[94:95] op_sel_hi:[1,0,1]
	v_pk_fma_f32 v[96:97], v[24:25], v[84:85], v[96:97] op_sel_hi:[1,0,1]
	v_pk_fma_f32 v[98:99], v[26:27], v[84:85], v[98:99] op_sel_hi:[1,0,1]
	v_pk_fma_f32 v[100:101], v[28:29], v[84:85], v[100:101] op_sel_hi:[1,0,1]
	v_pk_fma_f32 v[102:103], v[30:31], v[84:85], v[102:103] op_sel_hi:[1,0,1]
	s_waitcnt lgkmcnt(2)
	v_mfma_f32_32x32x16_bf16 v[16:31], v[76:79], v[0:3], 0
	v_mfma_f32_32x32x16_bf16 v[16:31], v[72:75], v[4:7], v[16:31]
	ds_read_b128 v[0:3], v165 offset:256
	ds_read_b128 v[4:7], v165 offset:288
	v_pk_mul_f32 v[32:33], v[32:33], v[112:113] clamp
	v_pk_mul_f32 v[34:35], v[34:35], v[112:113] clamp
	v_pk_mul_f32 v[36:37], v[36:37], v[112:113] clamp
	v_pk_mul_f32 v[38:39], v[38:39], v[112:113] clamp
	v_pk_mul_f32 v[40:41], v[40:41], v[112:113] clamp
	v_pk_mul_f32 v[42:43], v[42:43], v[112:113] clamp
	v_pk_mul_f32 v[44:45], v[44:45], v[112:113] clamp
	v_pk_mul_f32 v[46:47], v[46:47], v[112:113] clamp
	v_pk_fma_f32 v[88:89], v[32:33], v[108:109], v[88:89] op_sel_hi:[1,0,1]
	v_pk_fma_f32 v[90:91], v[34:35], v[108:109], v[90:91] op_sel_hi:[1,0,1]
	v_pk_fma_f32 v[92:93], v[36:37], v[108:109], v[92:93] op_sel_hi:[1,0,1]
	v_pk_fma_f32 v[94:95], v[38:39], v[108:109], v[94:95] op_sel_hi:[1,0,1]
	v_pk_fma_f32 v[96:97], v[40:41], v[108:109], v[96:97] op_sel_hi:[1,0,1]
	v_pk_fma_f32 v[98:99], v[42:43], v[108:109], v[98:99] op_sel_hi:[1,0,1]
	v_pk_fma_f32 v[100:101], v[44:45], v[108:109], v[100:101] op_sel_hi:[1,0,1]
	v_pk_fma_f32 v[102:103], v[46:47], v[108:109], v[102:103] op_sel_hi:[1,0,1]
	s_waitcnt lgkmcnt(2)
; __device__ __forceinline__ int bucketf(float f) { const unsigned u = __float_as_uint(f); const int idx = (int)((u >> 20) & 0x7FFu); const int c = min(max(idx - 816, 128), 255); return c ^ (((int)u >> 31) & 255); }
;     ...
;         { f32x16 zero16;
; #pragma unroll
;           for (int r = 0; r < 16; ++r) zero16[r] = 0.f;
;           f32x16 dA0, dA1, dB0, dB1; float wA0, wA1, wB0, wB1;
;           SW_MF(0, dA0, dA1, wA0, wA1);
;           SW_MF(1, dB0, dB1, wB0, wB1); __builtin_amdgcn_sched_barrier(0);
;           SW_VA(dA0, dA1, wA0, wA1);    __builtin_amdgcn_sched_barrier(0);
;           SW_MF(2, dA0, dA1, wA0, wA1); __builtin_amdgcn_sched_barrier(0);
;           SW_VA(dB0, dB1, wB0, wB1);    __builtin_amdgcn_sched_barrier(0);
;           SW_MF(3, dB0, dB1, wB0, wB1); __builtin_amdgcn_sched_barrier(0);
;           SW_VA(dA0, dA1, wA0, wA1);    __builtin_amdgcn_sched_barrier(0);
;           SW_VA(dB0, dB1, wB0, wB1); }
;     ...
;         f32x16 sc;
; #pragma unroll
;         for (int r = 0; r < 16; ++r) sc[r] = sc2[r >> 1][r & 1];
;         const unsigned s0 = (unsigned)(64 * kt + 32 * kb + 4 * hi);
; #pragma unroll
;         for (int r = 0; r < 16; ++r) { const unsigned s = s0 + (unsigned)((r & 3) + 8 * (r >> 2));
;             if (MODE == 5) { __hip_atomic_fetch_add(hist + 64 * bucketf(sc[r]), 1u, __ATOMIC_RELAXED, __HIP_MEMORY_SCOPE_WORKGROUP); continue; }
	v_mfma_f32_32x32x16_bf16 v[32:47], v[76:79], v[8:11], 0
	v_mfma_f32_32x32x16_bf16 v[32:47], v[72:75], v[12:15], v[32:47]
	ds_read_b128 v[8:11], v165 offset:320
	ds_read_b128 v[12:15], v165 offset:352
	v_pk_mul_f32 v[16:17], v[16:17], v[112:113] clamp
	v_pk_mul_f32 v[18:19], v[18:19], v[112:113] clamp
	v_pk_mul_f32 v[20:21], v[20:21], v[112:113] clamp
	v_pk_mul_f32 v[22:23], v[22:23], v[112:113] clamp
	v_pk_mul_f32 v[24:25], v[24:25], v[112:113] clamp
	v_pk_mul_f32 v[26:27], v[26:27], v[112:113] clamp
	v_pk_mul_f32 v[28:29], v[28:29], v[112:113] clamp
	v_pk_mul_f32 v[30:31], v[30:31], v[112:113] clamp
	v_pk_fma_f32 v[88:89], v[16:17], v[86:87], v[88:89] op_sel_hi:[1,0,1]
	v_pk_fma_f32 v[90:91], v[18:19], v[86:87], v[90:91] op_sel_hi:[1,0,1]
	v_pk_fma_f32 v[92:93], v[20:21], v[86:87], v[92:93] op_sel_hi:[1,0,1]
	v_pk_fma_f32 v[94:95], v[22:23], v[86:87], v[94:95] op_sel_hi:[1,0,1]
	v_pk_fma_f32 v[96:97], v[24:25], v[86:87], v[96:97] op_sel_hi:[1,0,1]
	v_pk_fma_f32 v[98:99], v[26:27], v[86:87], v[98:99] op_sel_hi:[1,0,1]
	v_pk_fma_f32 v[100:101], v[28:29], v[86:87], v[100:101] op_sel_hi:[1,0,1]
	v_pk_fma_f32 v[102:103], v[30:31], v[86:87], v[102:103] op_sel_hi:[1,0,1]
	v_pk_mul_f32 v[32:33], v[32:33], v[112:113] clamp
	v_pk_mul_f32 v[34:35], v[34:35], v[112:113] clamp
	v_pk_mul_f32 v[36:37], v[36:37], v[112:113] clamp
	v_pk_mul_f32 v[38:39], v[38:39], v[112:113] clamp
	v_pk_mul_f32 v[40:41], v[40:41], v[112:113] clamp
	v_pk_mul_f32 v[42:43], v[42:43], v[112:113] clamp
	v_pk_mul_f32 v[44:45], v[44:45], v[112:113] clamp
	v_pk_mul_f32 v[46:47], v[46:47], v[112:113] clamp
	v_pk_fma_f32 v[88:89], v[32:33], v[110:111], v[88:89] op_sel_hi:[1,0,1]
	v_pk_fma_f32 v[90:91], v[34:35], v[110:111], v[90:91] op_sel_hi:[1,0,1]
	v_pk_fma_f32 v[92:93], v[36:37], v[110:111], v[92:93] op_sel_hi:[1,0,1]
	v_pk_fma_f32 v[94:95], v[38:39], v[110:111], v[94:95] op_sel_hi:[1,0,1]
	v_pk_fma_f32 v[96:97], v[40:41], v[110:111], v[96:97] op_sel_hi:[1,0,1]
	v_pk_fma_f32 v[98:99], v[42:43], v[110:111], v[98:99] op_sel_hi:[1,0,1]
	v_pk_fma_f32 v[100:101], v[44:45], v[110:111], v[100:101] op_sel_hi:[1,0,1]
	v_pk_fma_f32 v[102:103], v[46:47], v[110:111], v[102:103] op_sel_hi:[1,0,1]
	s_waitcnt lgkmcnt(0)
	v_bfe_u32 v48, v88, 20, 11
	v_ashrrev_i32_e32 v49, 31, v88
	v_med3_u32 v48, v48, v117, v118
	v_bitop3_b32 v48, v48, v49, s56 bitop3:0x78
	v_lshl_add_u32 v48, v48, 8, v116
	ds_add_u32 v48, v222
	v_bfe_u32 v50, v89, 20, 11
	v_ashrrev_i32_e32 v51, 31, v89
	v_med3_u32 v50, v50, v117, v118
	v_bitop3_b32 v50, v50, v51, s56 bitop3:0x78
	v_lshl_add_u32 v50, v50, 8, v116
	ds_add_u32 v50, v222
	v_bfe_u32 v52, v90, 20, 11
	v_ashrrev_i32_e32 v53, 31, v90
	v_med3_u32 v52, v52, v117, v118
	v_bitop3_b32 v52, v52, v53, s56 bitop3:0x78
	v_lshl_add_u32 v52, v52, 8, v116
	ds_add_u32 v52, v222
	v_bfe_u32 v54, v91, 20, 11
	v_ashrrev_i32_e32 v55, 31, v91
	v_med3_u32 v54, v54, v117, v118
	v_bitop3_b32 v54, v54, v55, s56 bitop3:0x78
	v_lshl_add_u32 v54, v54, 8, v116
	ds_add_u32 v54, v222
	v_bfe_u32 v48, v92, 20, 11
	v_ashrrev_i32_e32 v49, 31, v92
	v_med3_u32 v48, v48, v117, v118
	v_bitop3_b32 v48, v48, v49, s56 bitop3:0x78
	v_lshl_add_u32 v48, v48, 8, v116
	ds_add_u32 v48, v222
	v_bfe_u32 v50, v93, 20, 11
	v_ashrrev_i32_e32 v51, 31, v93
	v_med3_u32 v50, v50, v117, v118
	v_bitop3_b32 v50, v50, v51, s56 bitop3:0x78
	v_lshl_add_u32 v50, v50, 8, v116
	ds_add_u32 v50, v222
	v_bfe_u32 v52, v94, 20, 11
	v_ashrrev_i32_e32 v53, 31, v94
	v_med3_u32 v52, v52, v117, v118
	v_bitop3_b32 v52, v52, v53, s56 bitop3:0x78
	v_lshl_add_u32 v52, v52, 8, v116
	ds_add_u32 v52, v222
	v_bfe_u32 v54, v95, 20, 11
	v_ashrrev_i32_e32 v55, 31, v95
	v_med3_u32 v54, v54, v117, v118
	v_bitop3_b32 v54, v54, v55, s56 bitop3:0x78
	v_lshl_add_u32 v54, v54, 8, v116
	ds_add_u32 v54, v222
	v_bfe_u32 v48, v96, 20, 11
	v_ashrrev_i32_e32 v49, 31, v96
	v_med3_u32 v48, v48, v117, v118
	v_bitop3_b32 v48, v48, v49, s56 bitop3:0x78
	v_lshl_add_u32 v48, v48, 8, v116
	ds_add_u32 v48, v222
	v_bfe_u32 v50, v97, 20, 11
	v_ashrrev_i32_e32 v51, 31, v97
	v_med3_u32 v50, v50, v117, v118
	v_bitop3_b32 v50, v50, v51, s56 bitop3:0x78
	v_lshl_add_u32 v50, v50, 8, v116
	ds_add_u32 v50, v222
	v_bfe_u32 v52, v98, 20, 11
	v_ashrrev_i32_e32 v53, 31, v98
	v_med3_u32 v52, v52, v117, v118
	v_bitop3_b32 v52, v52, v53, s56 bitop3:0x78
	v_lshl_add_u32 v52, v52, 8, v116
	ds_add_u32 v52, v222
	v_bfe_u32 v54, v99, 20, 11
	v_ashrrev_i32_e32 v55, 31, v99
	v_med3_u32 v54, v54, v117, v118
	v_bitop3_b32 v54, v54, v55, s56 bitop3:0x78
	v_lshl_add_u32 v54, v54, 8, v116
	ds_add_u32 v54, v222
	v_bfe_u32 v48, v100, 20, 11
	v_ashrrev_i32_e32 v49, 31, v100
	v_med3_u32 v48, v48, v117, v118
	v_bitop3_b32 v48, v48, v49, s56 bitop3:0x78
	v_lshl_add_u32 v48, v48, 8, v116
	ds_add_u32 v48, v222
	v_bfe_u32 v50, v101, 20, 11
	v_ashrrev_i32_e32 v51, 31, v101
	v_med3_u32 v50, v50, v117, v118
	v_bitop3_b32 v50, v50, v51, s56 bitop3:0x78
	v_lshl_add_u32 v50, v50, 8, v116
	ds_add_u32 v50, v222
	v_bfe_u32 v52, v102, 20, 11
	v_ashrrev_i32_e32 v53, 31, v102
	v_med3_u32 v52, v52, v117, v118
	v_bitop3_b32 v52, v52, v53, s56 bitop3:0x78
	v_lshl_add_u32 v52, v52, 8, v116
	ds_add_u32 v52, v222
	v_bfe_u32 v54, v103, 20, 11
	v_ashrrev_i32_e32 v55, 31, v103
	v_med3_u32 v54, v54, v117, v118
	v_bitop3_b32 v54, v54, v55, s56 bitop3:0x78
	v_lshl_add_u32 v54, v54, 8, v116
	ds_add_u32 v54, v222
	s_waitcnt vmcnt(0)
	v_mov_b64_e32 v[76:77], v[64:65]
	v_mov_b64_e32 v[78:79], v[66:67]
	v_mov_b64_e32 v[72:73], v[68:69]
	v_mov_b64_e32 v[74:75], v[70:71]
	s_cmp_lg_u32 s25, s1
	s_mov_b32 s2, s1
	s_cbranch_scc1 .Lm5_loop
	s_nop 0
	s_nop 0
	s_nop 0
	s_nop 0

;     ...
;     const int kt0 = wid >> 1; const int nit = kt0 <= c ? 2 * ((c - kt0) / 4 + 1) : 0;
;     const float t_lo = bucket_lo((int)pref), t_hi = bucket_lo((int)pref + 1);
;     const bf16_t* ikp = Zb + (size_t)(64 * kt0 + r32) * NZ + ZIK + hi * 8;
;     bf16x8 a0, a1;
;     if (nit > 0) { a0 = *(const bf16x8*)ikp; a1 = *(const bf16x8*)(ikp + 16); }
; #pragma unroll 1
;     for (int it = 0; it < nit; ++it) {
;         const int kt = kt0 + 4 * (it >> 1), kb = it & 1;
;         const int itn = it + 1 < nit ? it + 1 : it;
;         const bf16_t* np = ikp + (size_t)(256 * (itn >> 1) + 32 * (itn & 1)) * NZ; const bf16x8 n0 = *(const bf16x8*)np, n1 = *(const bf16x8*)(np + 16);
;         f32x2v sc2[8];
; #pragma unroll
;         for (int r = 0; r < 8; ++r) sc2[r] = (f32x2v){0.f, 0.f};
;     ...
;         { f32x16 zero16;
; #pragma unroll
;           for (int r = 0; r < 16; ++r) zero16[r] = 0.f;
;           f32x16 dA0, dA1, dB0, dB1; float wA0, wA1, wB0, wB1;
;           SW_MF(0, dA0, dA1, wA0, wA1);
;           SW_MF(1, dB0, dB1, wB0, wB1); __builtin_amdgcn_sched_barrier(0);
;           SW_VA(dA0, dA1, wA0, wA1);    __builtin_amdgcn_sched_barrier(0);
;           SW_MF(2, dA0, dA1, wA0, wA1); __builtin_amdgcn_sched_barrier(0);
;           SW_VA(dB0, dB1, wB0, wB1);    __builtin_amdgcn_sched_barrier(0);
;           SW_MF(3, dB0, dB1, wB0, wB1); __builtin_amdgcn_sched_barrier(0);
;           SW_VA(dA0, dA1, wA0, wA1);    __builtin_amdgcn_sched_barrier(0);
;           SW_VA(dB0, dB1, wB0, wB1); }
.LBB0_1521:
	s_and_b64 vcc, exec, s[18:19]
	s_cbranch_vccnz .LBB0_1620
	v_lshl_add_u32 v179, v169, 9, s57
	v_add_u32_e32 v180, s94, v171
	v_lshl_add_u32 v169, v169, 10, v200
	v_add_u32_e32 v171, s33, v171
	v_mul_f32_e32 v122, 0x2c800000, v154
	v_mul_f32_e32 v123, 0x2c800000, v178
	s_mov_b32 s18, 0
	v_mov_b32_e32 v112, 0x2c800000
	v_mov_b32_e32 v113, 0x2c800000
	ds_read2st64_b32 v[80:81], v167 offset1:1
	ds_read2st64_b32 v[82:83], v167 offset0:2 offset1:3
	ds_read2st64_b32 v[84:85], v167 offset0:4 offset1:5
	ds_read2st64_b32 v[86:87], v167 offset0:6 offset1:7
	ds_read_b128 v[48:51], v165
	ds_read_b128 v[52:55], v165 offset:32
	ds_read_b128 v[56:59], v165 offset:64
	ds_read_b128 v[60:63], v165 offset:96
	ds_read_b128 v[172:175], v165 offset:128
	ds_read_b128 v[232:235], v165 offset:160
	ds_read_b128 v[236:239], v165 offset:192
	ds_read_b128 v[136:139], v165 offset:224
	ds_read_b128 v[0:3], v165 offset:256
	ds_read_b128 v[4:7], v165 offset:288
	ds_read_b128 v[8:11], v165 offset:320
	ds_read_b128 v[12:15], v165 offset:352
	s_waitcnt lgkmcnt(12)
	v_mov_b32_e32 v104, v81
	v_mov_b32_e32 v106, v83
	v_mov_b32_e32 v108, v85
	v_mov_b32_e32 v110, v87
	s_waitcnt vmcnt(0) lgkmcnt(0)
	s_cmp_lt_u32 s69, 4
	s_cbranch_scc1 .Lstag_m6
	s_sleep 14
.Lstag_m6:
.Lm6_loop:
	v_mfma_f32_32x32x16_bf16 v[16:31], v[132:135], v[48:51], 0
	v_mfma_f32_32x32x16_bf16 v[16:31], v[128:131], v[52:55], v[16:31]
	v_mfma_f32_32x32x16_bf16 v[32:47], v[132:135], v[56:59], 0
	v_mfma_f32_32x32x16_bf16 v[32:47], v[128:131], v[60:63], v[32:47]
	s_add_i32 s1, s18, 1
	s_cmp_lt_u32 s1, s25
	s_cselect_b32 s3, s1, s18
	s_lshl_b32 vcc_lo, s3, 7
	s_and_b32 vcc_lo, vcc_lo, 0x7fffff00
	s_lshl_b32 s3, s3, 5
	s_and_b32 s3, s3, 32
	s_or_b32 s3, vcc_lo, s3
	v_mad_u64_u32 v[114:115], vcc, s3, v223, v[140:141]
	s_lshr_b32 s0, s18, 1
	s_lshl_b32 s0, s0, 2
	s_add_i32 s0, s0, s24
	s_lshl_b32 s0, s0, 6
	s_and_b32 s2, s18, 1
	s_lshl_b32 s2, s2, 5
	s_or_b32 s0, s0, s2
	v_or_b32_e32 v124, s0, v159
	global_load_dwordx4 v[64:67], v[114:115], off
	global_load_dwordx4 v[68:71], v[114:115], off offset:32
	v_pk_mul_f32 v[16:17], v[16:17], v[112:113] clamp
	v_pk_mul_f32 v[18:19], v[18:19], v[112:113] clamp
	v_pk_mul_f32 v[20:21], v[20:21], v[112:113] clamp
	v_pk_mul_f32 v[22:23], v[22:23], v[112:113] clamp
	v_pk_mul_f32 v[24:25], v[24:25], v[112:113] clamp
	v_pk_mul_f32 v[26:27], v[26:27], v[112:113] clamp
	v_pk_mul_f32 v[28:29], v[28:29], v[112:113] clamp
	v_pk_mul_f32 v[30:31], v[30:31], v[112:113] clamp
	v_pk_fma_f32 v[88:89], v[16:17], v[80:81], 0 op_sel_hi:[1,0,0]
	v_pk_fma_f32 v[90:91], v[18:19], v[80:81], 0 op_sel_hi:[1,0,0]
	v_pk_fma_f32 v[92:93], v[20:21], v[80:81], 0 op_sel_hi:[1,0,0]
	v_pk_fma_f32 v[94:95], v[22:23], v[80:81], 0 op_sel_hi:[1,0,0]
	v_pk_fma_f32 v[96:97], v[24:25], v[80:81], 0 op_sel_hi:[1,0,0]
	v_pk_fma_f32 v[98:99], v[26:27], v[80:81], 0 op_sel_hi:[1,0,0]
	v_pk_fma_f32 v[100:101], v[28:29], v[80:81], 0 op_sel_hi:[1,0,0]
	v_pk_fma_f32 v[102:103], v[30:31], v[80:81], 0 op_sel_hi:[1,0,0]
	v_mfma_f32_32x32x16_bf16 v[16:31], v[132:135], v[172:175], 0
	v_mfma_f32_32x32x16_bf16 v[16:31], v[128:131], v[232:235], v[16:31]
	v_pk_mul_f32 v[32:33], v[32:33], v[112:113] clamp
	v_pk_mul_f32 v[34:35], v[34:35], v[112:113] clamp
	v_pk_mul_f32 v[36:37], v[36:37], v[112:113] clamp
	v_pk_mul_f32 v[38:39], v[38:39], v[112:113] clamp
	v_pk_mul_f32 v[40:41], v[40:41], v[112:113] clamp
	v_pk_mul_f32 v[42:43], v[42:43], v[112:113] clamp
	v_pk_mul_f32 v[44:45], v[44:45], v[112:113] clamp
	v_pk_mul_f32 v[46:47], v[46:47], v[112:113] clamp
	v_pk_fma_f32 v[88:89], v[32:33], v[104:105], v[88:89] op_sel_hi:[1,0,1]
	v_pk_fma_f32 v[90:91], v[34:35], v[104:105], v[90:91] op_sel_hi:[1,0,1]
	v_pk_fma_f32 v[92:93], v[36:37], v[104:105], v[92:93] op_sel_hi:[1,0,1]
	v_pk_fma_f32 v[94:95], v[38:39], v[104:105], v[94:95] op_sel_hi:[1,0,1]
	v_pk_fma_f32 v[96:97], v[40:41], v[104:105], v[96:97] op_sel_hi:[1,0,1]
	v_pk_fma_f32 v[98:99], v[42:43], v[104:105], v[98:99] op_sel_hi:[1,0,1]
	v_pk_fma_f32 v[100:101], v[44:45], v[104:105], v[100:101] op_sel_hi:[1,0,1]
	v_pk_fma_f32 v[102:103], v[46:47], v[104:105], v[102:103] op_sel_hi:[1,0,1]
	v_mfma_f32_32x32x16_bf16 v[32:47], v[132:135], v[236:239], 0
	v_mfma_f32_32x32x16_bf16 v[32:47], v[128:131], v[136:139], v[32:47]
	v_pk_mul_f32 v[16:17], v[16:17], v[112:113] clamp
	v_pk_mul_f32 v[18:19], v[18:19], v[112:113] clamp
	v_pk_mul_f32 v[20:21], v[20:21], v[112:113] clamp
	v_pk_mul_f32 v[22:23], v[22:23], v[112:113] clamp
	v_pk_mul_f32 v[24:25], v[24:25], v[112:113] clamp
	v_pk_mul_f32 v[26:27], v[26:27], v[112:113] clamp
	v_pk_mul_f32 v[28:29], v[28:29], v[112:113] clamp
	v_pk_mul_f32 v[30:31], v[30:31], v[112:113] clamp
	v_pk_fma_f32 v[88:89], v[16:17], v[82:83], v[88:89] op_sel_hi:[1,0,1]
	v_pk_fma_f32 v[90:91], v[18:19], v[82:83], v[90:91] op_sel_hi:[1,0,1]
	v_pk_fma_f32 v[92:93], v[20:21], v[82:83], v[92:93] op_sel_hi:[1,0,1]
	v_pk_fma_f32 v[94:95], v[22:23], v[82:83], v[94:95] op_sel_hi:[1,0,1]
	v_pk_fma_f32 v[96:97], v[24:25], v[82:83], v[96:97] op_sel_hi:[1,0,1]
	v_pk_fma_f32 v[98:99], v[26:27], v[82:83], v[98:99] op_sel_hi:[1,0,1]
	v_pk_fma_f32 v[100:101], v[28:29], v[82:83], v[100:101] op_sel_hi:[1,0,1]
	v_pk_fma_f32 v[102:103], v[30:31], v[82:83], v[102:103] op_sel_hi:[1,0,1]
	v_mfma_f32_32x32x16_bf16 v[16:31], v[132:135], v[0:3], 0
	v_mfma_f32_32x32x16_bf16 v[16:31], v[128:131], v[4:7], v[16:31]
	ds_read_b128 v[0:3], v165 offset:384
	ds_read_b128 v[4:7], v165 offset:416
	v_pk_mul_f32 v[32:33], v[32:33], v[112:113] clamp
	v_pk_mul_f32 v[34:35], v[34:35], v[112:113] clamp
	v_pk_mul_f32 v[36:37], v[36:37], v[112:113] clamp
	v_pk_mul_f32 v[38:39], v[38:39], v[112:113] clamp
; __device__ __forceinline__ unsigned sortable(float f) { const unsigned u = __float_as_uint(f); return u ^ ((unsigned)((int)u >> 31) | 0x80000000u); }
; __device__ __forceinline__ int bucketf(float f) { const unsigned u = __float_as_uint(f); const int idx = (int)((u >> 20) & 0x7FFu); const int c = min(max(idx - 816, 128), 255); return c ^ (((int)u >> 31) & 255); }
;     ...
;         { f32x16 zero16;
; #pragma unroll
;           for (int r = 0; r < 16; ++r) zero16[r] = 0.f;
;           f32x16 dA0, dA1, dB0, dB1; float wA0, wA1, wB0, wB1;
;           SW_MF(0, dA0, dA1, wA0, wA1);
;           SW_MF(1, dB0, dB1, wB0, wB1); __builtin_amdgcn_sched_barrier(0);
;           SW_VA(dA0, dA1, wA0, wA1);    __builtin_amdgcn_sched_barrier(0);
;           SW_MF(2, dA0, dA1, wA0, wA1); __builtin_amdgcn_sched_barrier(0);
;           SW_VA(dB0, dB1, wB0, wB1);    __builtin_amdgcn_sched_barrier(0);
;           SW_MF(3, dB0, dB1, wB0, wB1); __builtin_amdgcn_sched_barrier(0);
;           SW_VA(dA0, dA1, wA0, wA1);    __builtin_amdgcn_sched_barrier(0);
;           SW_VA(dB0, dB1, wB0, wB1); }
;     ...
;         f32x16 sc;
; #pragma unroll
;         for (int r = 0; r < 16; ++r) sc[r] = sc2[r >> 1][r & 1];
;         const unsigned s0 = (unsigned)(64 * kt + 32 * kb + 4 * hi);
; #pragma unroll
;         for (int r = 0; r < 16; ++r) { const unsigned s = s0 + (unsigned)((r & 3) + 8 * (r >> 2));
;             if (MODE == 5) { __hip_atomic_fetch_add(hist + 64 * bucketf(sc[r]), 1u, __ATOMIC_RELAXED, __HIP_MEMORY_SCOPE_WORKGROUP); continue; }
;             if (MODE == 6) {
;                 if (sc[r] >= t_hi) { const unsigned pos = __hip_atomic_fetch_add(cnt, 1u, __ATOMIC_RELAXED, __HIP_MEMORY_SCOPE_WORKGROUP); sel[pos & 255u] = (unsigned short)s; }
;                 else if (sc[r] >= t_lo) { const unsigned key = (sortable(sc[r]) & 0xFFFFE000u) | (8191u - s);
;                     const unsigned pos = __hip_atomic_fetch_add(ccnt, 1u, __ATOMIC_RELAXED, __HIP_MEMORY_SCOPE_WORKGROUP); cand[pos & (DS_CAP - 1)] = key; }
	v_pk_mul_f32 v[40:41], v[40:41], v[112:113] clamp
	v_pk_mul_f32 v[42:43], v[42:43], v[112:113] clamp
	v_pk_mul_f32 v[44:45], v[44:45], v[112:113] clamp
	v_pk_mul_f32 v[46:47], v[46:47], v[112:113] clamp
	v_pk_fma_f32 v[88:89], v[32:33], v[106:107], v[88:89] op_sel_hi:[1,0,1]
	v_pk_fma_f32 v[90:91], v[34:35], v[106:107], v[90:91] op_sel_hi:[1,0,1]
	v_pk_fma_f32 v[92:93], v[36:37], v[106:107], v[92:93] op_sel_hi:[1,0,1]
	v_pk_fma_f32 v[94:95], v[38:39], v[106:107], v[94:95] op_sel_hi:[1,0,1]
	v_pk_fma_f32 v[96:97], v[40:41], v[106:107], v[96:97] op_sel_hi:[1,0,1]
	v_pk_fma_f32 v[98:99], v[42:43], v[106:107], v[98:99] op_sel_hi:[1,0,1]
	v_pk_fma_f32 v[100:101], v[44:45], v[106:107], v[100:101] op_sel_hi:[1,0,1]
	v_pk_fma_f32 v[102:103], v[46:47], v[106:107], v[102:103] op_sel_hi:[1,0,1]
	v_mfma_f32_32x32x16_bf16 v[32:47], v[132:135], v[8:11], 0
	v_mfma_f32_32x32x16_bf16 v[32:47], v[128:131], v[12:15], v[32:47]
	ds_read_b128 v[8:11], v165 offset:448
	ds_read_b128 v[12:15], v165 offset:480
	v_pk_mul_f32 v[16:17], v[16:17], v[112:113] clamp
	v_pk_mul_f32 v[18:19], v[18:19], v[112:113] clamp
	v_pk_mul_f32 v[20:21], v[20:21], v[112:113] clamp
	v_pk_mul_f32 v[22:23], v[22:23], v[112:113] clamp
	v_pk_mul_f32 v[24:25], v[24:25], v[112:113] clamp
	v_pk_mul_f32 v[26:27], v[26:27], v[112:113] clamp
	v_pk_mul_f32 v[28:29], v[28:29], v[112:113] clamp
	v_pk_mul_f32 v[30:31], v[30:31], v[112:113] clamp
	v_pk_fma_f32 v[88:89], v[16:17], v[84:85], v[88:89] op_sel_hi:[1,0,1]
	v_pk_fma_f32 v[90:91], v[18:19], v[84:85], v[90:91] op_sel_hi:[1,0,1]
	v_pk_fma_f32 v[92:93], v[20:21], v[84:85], v[92:93] op_sel_hi:[1,0,1]
	v_pk_fma_f32 v[94:95], v[22:23], v[84:85], v[94:95] op_sel_hi:[1,0,1]
	v_pk_fma_f32 v[96:97], v[24:25], v[84:85], v[96:97] op_sel_hi:[1,0,1]
	v_pk_fma_f32 v[98:99], v[26:27], v[84:85], v[98:99] op_sel_hi:[1,0,1]
	v_pk_fma_f32 v[100:101], v[28:29], v[84:85], v[100:101] op_sel_hi:[1,0,1]
	v_pk_fma_f32 v[102:103], v[30:31], v[84:85], v[102:103] op_sel_hi:[1,0,1]
	s_waitcnt lgkmcnt(2)
	v_mfma_f32_32x32x16_bf16 v[16:31], v[132:135], v[0:3], 0
	v_mfma_f32_32x32x16_bf16 v[16:31], v[128:131], v[4:7], v[16:31]
	ds_read_b128 v[0:3], v165 offset:256
	ds_read_b128 v[4:7], v165 offset:288
	v_pk_mul_f32 v[32:33], v[32:33], v[112:113] clamp
	v_pk_mul_f32 v[34:35], v[34:35], v[112:113] clamp
	v_pk_mul_f32 v[36:37], v[36:37], v[112:113] clamp
	v_pk_mul_f32 v[38:39], v[38:39], v[112:113] clamp
	v_pk_mul_f32 v[40:41], v[40:41], v[112:113] clamp
	v_pk_mul_f32 v[42:43], v[42:43], v[112:113] clamp
	v_pk_mul_f32 v[44:45], v[44:45], v[112:113] clamp
	v_pk_mul_f32 v[46:47], v[46:47], v[112:113] clamp
	v_pk_fma_f32 v[88:89], v[32:33], v[108:109], v[88:89] op_sel_hi:[1,0,1]
	v_pk_fma_f32 v[90:91], v[34:35], v[108:109], v[90:91] op_sel_hi:[1,0,1]
	v_pk_fma_f32 v[92:93], v[36:37], v[108:109], v[92:93] op_sel_hi:[1,0,1]
	v_pk_fma_f32 v[94:95], v[38:39], v[108:109], v[94:95] op_sel_hi:[1,0,1]
	v_pk_fma_f32 v[96:97], v[40:41], v[108:109], v[96:97] op_sel_hi:[1,0,1]
	v_pk_fma_f32 v[98:99], v[42:43], v[108:109], v[98:99] op_sel_hi:[1,0,1]
	v_pk_fma_f32 v[100:101], v[44:45], v[108:109], v[100:101] op_sel_hi:[1,0,1]
	v_pk_fma_f32 v[102:103], v[46:47], v[108:109], v[102:103] op_sel_hi:[1,0,1]
	s_waitcnt lgkmcnt(2)
	v_mfma_f32_32x32x16_bf16 v[32:47], v[132:135], v[8:11], 0
	v_mfma_f32_32x32x16_bf16 v[32:47], v[128:131], v[12:15], v[32:47]
	ds_read_b128 v[8:11], v165 offset:320
	ds_read_b128 v[12:15], v165 offset:352
	v_pk_mul_f32 v[16:17], v[16:17], v[112:113] clamp
	v_pk_mul_f32 v[18:19], v[18:19], v[112:113] clamp
	v_pk_mul_f32 v[20:21], v[20:21], v[112:113] clamp
	v_pk_mul_f32 v[22:23], v[22:23], v[112:113] clamp
	v_pk_mul_f32 v[24:25], v[24:25], v[112:113] clamp
	v_pk_mul_f32 v[26:27], v[26:27], v[112:113] clamp
	v_pk_mul_f32 v[28:29], v[28:29], v[112:113] clamp
	v_pk_mul_f32 v[30:31], v[30:31], v[112:113] clamp
	v_pk_fma_f32 v[88:89], v[16:17], v[86:87], v[88:89] op_sel_hi:[1,0,1]
	v_pk_fma_f32 v[90:91], v[18:19], v[86:87], v[90:91] op_sel_hi:[1,0,1]
	v_pk_fma_f32 v[92:93], v[20:21], v[86:87], v[92:93] op_sel_hi:[1,0,1]
	v_pk_fma_f32 v[94:95], v[22:23], v[86:87], v[94:95] op_sel_hi:[1,0,1]
	v_pk_fma_f32 v[96:97], v[24:25], v[86:87], v[96:97] op_sel_hi:[1,0,1]
	v_pk_fma_f32 v[98:99], v[26:27], v[86:87], v[98:99] op_sel_hi:[1,0,1]
	v_pk_fma_f32 v[100:101], v[28:29], v[86:87], v[100:101] op_sel_hi:[1,0,1]
	v_pk_fma_f32 v[102:103], v[30:31], v[86:87], v[102:103] op_sel_hi:[1,0,1]
	v_pk_mul_f32 v[32:33], v[32:33], v[112:113] clamp
	v_pk_mul_f32 v[34:35], v[34:35], v[112:113] clamp
	v_pk_mul_f32 v[36:37], v[36:37], v[112:113] clamp
	v_pk_mul_f32 v[38:39], v[38:39], v[112:113] clamp
	v_pk_mul_f32 v[40:41], v[40:41], v[112:113] clamp
	v_pk_mul_f32 v[42:43], v[42:43], v[112:113] clamp
	v_pk_mul_f32 v[44:45], v[44:45], v[112:113] clamp
	v_pk_mul_f32 v[46:47], v[46:47], v[112:113] clamp
	v_pk_fma_f32 v[88:89], v[32:33], v[110:111], v[88:89] op_sel_hi:[1,0,1]
	v_pk_fma_f32 v[90:91], v[34:35], v[110:111], v[90:91] op_sel_hi:[1,0,1]
	v_pk_fma_f32 v[92:93], v[36:37], v[110:111], v[92:93] op_sel_hi:[1,0,1]
	v_pk_fma_f32 v[94:95], v[38:39], v[110:111], v[94:95] op_sel_hi:[1,0,1]
	v_pk_fma_f32 v[96:97], v[40:41], v[110:111], v[96:97] op_sel_hi:[1,0,1]
	v_pk_fma_f32 v[98:99], v[42:43], v[110:111], v[98:99] op_sel_hi:[1,0,1]
	v_pk_fma_f32 v[100:101], v[44:45], v[110:111], v[100:101] op_sel_hi:[1,0,1]
	v_pk_fma_f32 v[102:103], v[46:47], v[110:111], v[102:103] op_sel_hi:[1,0,1]
	s_waitcnt lgkmcnt(0)
	v_cmp_ge_f32_e64 s[40:41], v88, v122
	v_cmp_ge_f32_e64 s[42:43], v88, v123
	v_mov_b32_e32 v18, v124
	v_cndmask_b32_e64 v119, v171, v180, s[40:41]
	s_mov_b64 exec, s[42:43]
	ds_add_rtn_u32 v16, v119, v222
	s_andn2_b64 s[42:43], s[42:43], s[40:41]
	s_mov_b64 exec, -1
	v_cmp_ge_f32_e64 s[44:45], v89, v122
	v_cmp_ge_f32_e64 s[22:23], v89, v123
	v_or_b32_e32 v19, 1, v124
	v_cndmask_b32_e64 v120, v171, v180, s[44:45]
	s_mov_b64 exec, s[22:23]
	ds_add_rtn_u32 v17, v120, v222
	s_andn2_b64 s[22:23], s[22:23], s[44:45]
	s_mov_b64 exec, -1
	v_cmp_ge_f32_e64 s[20:21], v90, v122
	v_cmp_ge_f32_e64 s[2:3], v90, v123
	v_or_b32_e32 v24, 2, v124
	v_cndmask_b32_e64 v121, v171, v180, s[20:21]
	s_mov_b64 exec, s[2:3]
	ds_add_rtn_u32 v23, v121, v222
	s_andn2_b64 s[2:3], s[2:3], s[20:21]
	s_mov_b64 exec, -1
	s_waitcnt lgkmcnt(2)
	v_and_b32_e32 v16, 0xff, v16
	s_mov_b64 exec, s[40:41]
	v_lshl_add_u32 v20, v16, 1, v179
	ds_write_b16 v20, v18
	s_mov_b64 exec, s[42:43]
	s_cbranch_execz .Lm6_nb0
	v_ashrrev_i32_e32 v22, 31, v88
	v_sub_u32_e32 v18, 0x1fff, v18
	v_lshl_add_u32 v20, v16, 2, v169
	v_bitop3_b32 v21, v22, v88, s64 bitop3:0x36
	v_and_or_b32 v21, v21, s65, v18
	ds_write_b32 v20, v21
; __device__ __forceinline__ unsigned sortable(float f) { const unsigned u = __float_as_uint(f); return u ^ ((unsigned)((int)u >> 31) | 0x80000000u); }
; __device__ __forceinline__ int bucketf(float f) { const unsigned u = __float_as_uint(f); const int idx = (int)((u >> 20) & 0x7FFu); const int c = min(max(idx - 816, 128), 255); return c ^ (((int)u >> 31) & 255); }
;     ...
;         for (int r = 0; r < 16; ++r) { const unsigned s = s0 + (unsigned)((r & 3) + 8 * (r >> 2));
;             if (MODE == 5) { __hip_atomic_fetch_add(hist + 64 * bucketf(sc[r]), 1u, __ATOMIC_RELAXED, __HIP_MEMORY_SCOPE_WORKGROUP); continue; }
;             if (MODE == 6) {
;                 if (sc[r] >= t_hi) { const unsigned pos = __hip_atomic_fetch_add(cnt, 1u, __ATOMIC_RELAXED, __HIP_MEMORY_SCOPE_WORKGROUP); sel[pos & 255u] = (unsigned short)s; }
;                 else if (sc[r] >= t_lo) { const unsigned key = (sortable(sc[r]) & 0xFFFFE000u) | (8191u - s);
;                     const unsigned pos = __hip_atomic_fetch_add(ccnt, 1u, __ATOMIC_RELAXED, __HIP_MEMORY_SCOPE_WORKGROUP); cand[pos & (DS_CAP - 1)] = key; }
;                 continue; }
.Lm6_nb0:
	s_mov_b64 exec, -1
	v_cmp_ge_f32_e64 s[40:41], v91, v122
	v_cmp_ge_f32_e64 s[42:43], v91, v123
	v_or_b32_e32 v18, 3, v124
	v_cndmask_b32_e64 v119, v171, v180, s[40:41]
	s_mov_b64 exec, s[42:43]
	ds_add_rtn_u32 v16, v119, v222
	s_andn2_b64 s[42:43], s[42:43], s[40:41]
	s_mov_b64 exec, -1
	s_waitcnt lgkmcnt(3)
	v_and_b32_e32 v17, 0xff, v17
	s_mov_b64 exec, s[44:45]
	v_lshl_add_u32 v20, v17, 1, v179
	ds_write_b16 v20, v19
	s_mov_b64 exec, s[22:23]
	s_cbranch_execz .Lm6_nb1
	v_ashrrev_i32_e32 v22, 31, v89
	v_sub_u32_e32 v19, 0x1fff, v19
	v_lshl_add_u32 v20, v17, 2, v169
	v_bitop3_b32 v21, v22, v89, s64 bitop3:0x36
	v_and_or_b32 v21, v21, s65, v19
	ds_write_b32 v20, v21
.Lm6_nb1:
	s_mov_b64 exec, -1
	v_cmp_ge_f32_e64 s[44:45], v92, v122
	v_cmp_ge_f32_e64 s[22:23], v92, v123
	v_or_b32_e32 v19, 8, v124
	v_cndmask_b32_e64 v120, v171, v180, s[44:45]
	s_mov_b64 exec, s[22:23]
	ds_add_rtn_u32 v17, v120, v222
	s_andn2_b64 s[22:23], s[22:23], s[44:45]
	s_mov_b64 exec, -1
	s_waitcnt lgkmcnt(4)
	v_and_b32_e32 v23, 0xff, v23
	s_mov_b64 exec, s[20:21]
	v_lshl_add_u32 v20, v23, 1, v179
	ds_write_b16 v20, v24
	s_mov_b64 exec, s[2:3]
	s_cbranch_execz .Lm6_nb2
	v_ashrrev_i32_e32 v22, 31, v90
	v_sub_u32_e32 v24, 0x1fff, v24
	v_lshl_add_u32 v20, v23, 2, v169
	v_bitop3_b32 v21, v22, v90, s64 bitop3:0x36
	v_and_or_b32 v21, v21, s65, v24
	ds_write_b32 v20, v21
.Lm6_nb2:
	s_mov_b64 exec, -1
	v_cmp_ge_f32_e64 s[20:21], v93, v122
	v_cmp_ge_f32_e64 s[2:3], v93, v123
	v_or_b32_e32 v24, 9, v124
	v_cndmask_b32_e64 v121, v171, v180, s[20:21]
	s_mov_b64 exec, s[2:3]
	ds_add_rtn_u32 v23, v121, v222
	s_andn2_b64 s[2:3], s[2:3], s[20:21]
	s_mov_b64 exec, -1
	s_waitcnt lgkmcnt(4)
	v_and_b32_e32 v16, 0xff, v16
	s_mov_b64 exec, s[40:41]
	v_lshl_add_u32 v20, v16, 1, v179
	ds_write_b16 v20, v18
	s_mov_b64 exec, s[42:43]
	s_cbranch_execz .Lm6_nb3
	v_ashrrev_i32_e32 v22, 31, v91
	v_sub_u32_e32 v18, 0x1fff, v18
	v_lshl_add_u32 v20, v16, 2, v169
	v_bitop3_b32 v21, v22, v91, s64 bitop3:0x36
	v_and_or_b32 v21, v21, s65, v18
	ds_write_b32 v20, v21
.Lm6_nb3:
	s_mov_b64 exec, -1
	v_cmp_ge_f32_e64 s[40:41], v94, v122
	v_cmp_ge_f32_e64 s[42:43], v94, v123
	v_or_b32_e32 v18, 10, v124
	v_cndmask_b32_e64 v119, v171, v180, s[40:41]
	s_mov_b64 exec, s[42:43]
	ds_add_rtn_u32 v16, v119, v222
	s_andn2_b64 s[42:43], s[42:43], s[40:41]
	s_mov_b64 exec, -1
	s_waitcnt lgkmcnt(4)
	v_and_b32_e32 v17, 0xff, v17
	s_mov_b64 exec, s[44:45]
	v_lshl_add_u32 v20, v17, 1, v179
	ds_write_b16 v20, v19
	s_mov_b64 exec, s[22:23]
	s_cbranch_execz .Lm6_nb4
	v_ashrrev_i32_e32 v22, 31, v92
	v_sub_u32_e32 v19, 0x1fff, v19
	v_lshl_add_u32 v20, v17, 2, v169
	v_bitop3_b32 v21, v22, v92, s64 bitop3:0x36
	v_and_or_b32 v21, v21, s65, v19
	ds_write_b32 v20, v21
.Lm6_nb4:
	s_mov_b64 exec, -1
	v_cmp_ge_f32_e64 s[44:45], v95, v122
	v_cmp_ge_f32_e64 s[22:23], v95, v123
	v_or_b32_e32 v19, 11, v124
	v_cndmask_b32_e64 v120, v171, v180, s[44:45]
	s_mov_b64 exec, s[22:23]
	ds_add_rtn_u32 v17, v120, v222
	s_andn2_b64 s[22:23], s[22:23], s[44:45]
	s_mov_b64 exec, -1
	s_waitcnt lgkmcnt(4)
	v_and_b32_e32 v23, 0xff, v23
	s_mov_b64 exec, s[20:21]
	v_lshl_add_u32 v20, v23, 1, v179
	ds_write_b16 v20, v24
	s_mov_b64 exec, s[2:3]
	s_cbranch_execz .Lm6_nb5
	v_ashrrev_i32_e32 v22, 31, v93
	v_sub_u32_e32 v24, 0x1fff, v24
	v_lshl_add_u32 v20, v23, 2, v169
	v_bitop3_b32 v21, v22, v93, s64 bitop3:0x36
	v_and_or_b32 v21, v21, s65, v24
	ds_write_b32 v20, v21
.Lm6_nb5:
	s_mov_b64 exec, -1
	v_cmp_ge_f32_e64 s[20:21], v96, v122
	v_cmp_ge_f32_e64 s[2:3], v96, v123
	v_or_b32_e32 v24, 16, v124
	v_cndmask_b32_e64 v121, v171, v180, s[20:21]
	s_mov_b64 exec, s[2:3]
	ds_add_rtn_u32 v23, v121, v222
	s_andn2_b64 s[2:3], s[2:3], s[20:21]
	s_mov_b64 exec, -1
	s_waitcnt lgkmcnt(4)
	v_and_b32_e32 v16, 0xff, v16
	s_mov_b64 exec, s[40:41]
	v_lshl_add_u32 v20, v16, 1, v179
	ds_write_b16 v20, v18
	s_mov_b64 exec, s[42:43]
	s_cbranch_execz .Lm6_nb6
	v_ashrrev_i32_e32 v22, 31, v94
	v_sub_u32_e32 v18, 0x1fff, v18
	v_lshl_add_u32 v20, v16, 2, v169
	v_bitop3_b32 v21, v22, v94, s64 bitop3:0x36
	v_and_or_b32 v21, v21, s65, v18
	ds_write_b32 v20, v21
.Lm6_nb6:
	s_mov_b64 exec, -1
	v_cmp_ge_f32_e64 s[40:41], v97, v122
	v_cmp_ge_f32_e64 s[42:43], v97, v123
	v_or_b32_e32 v18, 17, v124
	v_cndmask_b32_e64 v119, v171, v180, s[40:41]
	s_mov_b64 exec, s[42:43]
	ds_add_rtn_u32 v16, v119, v222
	s_andn2_b64 s[42:43], s[42:43], s[40:41]
	s_mov_b64 exec, -1
	s_waitcnt lgkmcnt(4)
	v_and_b32_e32 v17, 0xff, v17
	s_mov_b64 exec, s[44:45]
	v_lshl_add_u32 v20, v17, 1, v179
	ds_write_b16 v20, v19
	s_mov_b64 exec, s[22:23]
	s_cbranch_execz .Lm6_nb7
	v_ashrrev_i32_e32 v22, 31, v95
	v_sub_u32_e32 v19, 0x1fff, v19
	v_lshl_add_u32 v20, v17, 2, v169
	v_bitop3_b32 v21, v22, v95, s64 bitop3:0x36
	v_and_or_b32 v21, v21, s65, v19
	ds_write_b32 v20, v21
; __device__ __forceinline__ unsigned sortable(float f) { const unsigned u = __float_as_uint(f); return u ^ ((unsigned)((int)u >> 31) | 0x80000000u); }
; __device__ __forceinline__ int bucketf(float f) { const unsigned u = __float_as_uint(f); const int idx = (int)((u >> 20) & 0x7FFu); const int c = min(max(idx - 816, 128), 255); return c ^ (((int)u >> 31) & 255); }
;     ...
;         const unsigned s0 = (unsigned)(64 * kt + 32 * kb + 4 * hi);
; #pragma unroll
;         for (int r = 0; r < 16; ++r) { const unsigned s = s0 + (unsigned)((r & 3) + 8 * (r >> 2));
;             if (MODE == 5) { __hip_atomic_fetch_add(hist + 64 * bucketf(sc[r]), 1u, __ATOMIC_RELAXED, __HIP_MEMORY_SCOPE_WORKGROUP); continue; }
;             if (MODE == 6) {
;                 if (sc[r] >= t_hi) { const unsigned pos = __hip_atomic_fetch_add(cnt, 1u, __ATOMIC_RELAXED, __HIP_MEMORY_SCOPE_WORKGROUP); sel[pos & 255u] = (unsigned short)s; }
;                 else if (sc[r] >= t_lo) { const unsigned key = (sortable(sc[r]) & 0xFFFFE000u) | (8191u - s);
;                     const unsigned pos = __hip_atomic_fetch_add(ccnt, 1u, __ATOMIC_RELAXED, __HIP_MEMORY_SCOPE_WORKGROUP); cand[pos & (DS_CAP - 1)] = key; }
;                 continue; }
.Lm6_nb7:
	s_mov_b64 exec, -1
	v_cmp_ge_f32_e64 s[44:45], v98, v122
	v_cmp_ge_f32_e64 s[22:23], v98, v123
	v_or_b32_e32 v19, 18, v124
	v_cndmask_b32_e64 v120, v171, v180, s[44:45]
	s_mov_b64 exec, s[22:23]
	ds_add_rtn_u32 v17, v120, v222
	s_andn2_b64 s[22:23], s[22:23], s[44:45]
	s_mov_b64 exec, -1
	s_waitcnt lgkmcnt(4)
	v_and_b32_e32 v23, 0xff, v23
	s_mov_b64 exec, s[20:21]
	v_lshl_add_u32 v20, v23, 1, v179
	ds_write_b16 v20, v24
	s_mov_b64 exec, s[2:3]
	s_cbranch_execz .Lm6_nb8
	v_ashrrev_i32_e32 v22, 31, v96
	v_sub_u32_e32 v24, 0x1fff, v24
	v_lshl_add_u32 v20, v23, 2, v169
	v_bitop3_b32 v21, v22, v96, s64 bitop3:0x36
	v_and_or_b32 v21, v21, s65, v24
	ds_write_b32 v20, v21
.Lm6_nb8:
	s_mov_b64 exec, -1
	v_cmp_ge_f32_e64 s[20:21], v99, v122
	v_cmp_ge_f32_e64 s[2:3], v99, v123
	v_or_b32_e32 v24, 19, v124
	v_cndmask_b32_e64 v121, v171, v180, s[20:21]
	s_mov_b64 exec, s[2:3]
	ds_add_rtn_u32 v23, v121, v222
	s_andn2_b64 s[2:3], s[2:3], s[20:21]
	s_mov_b64 exec, -1
	s_waitcnt lgkmcnt(4)
	v_and_b32_e32 v16, 0xff, v16
	s_mov_b64 exec, s[40:41]
	v_lshl_add_u32 v20, v16, 1, v179
	ds_write_b16 v20, v18
	s_mov_b64 exec, s[42:43]
	s_cbranch_execz .Lm6_nb9
	v_ashrrev_i32_e32 v22, 31, v97
	v_sub_u32_e32 v18, 0x1fff, v18
	v_lshl_add_u32 v20, v16, 2, v169
	v_bitop3_b32 v21, v22, v97, s64 bitop3:0x36
	v_and_or_b32 v21, v21, s65, v18
	ds_write_b32 v20, v21
.Lm6_nb9:
	s_mov_b64 exec, -1
	v_cmp_ge_f32_e64 s[40:41], v100, v122
	v_cmp_ge_f32_e64 s[42:43], v100, v123
	v_or_b32_e32 v18, 24, v124
	v_cndmask_b32_e64 v119, v171, v180, s[40:41]
	s_mov_b64 exec, s[42:43]
	ds_add_rtn_u32 v16, v119, v222
	s_andn2_b64 s[42:43], s[42:43], s[40:41]
	s_mov_b64 exec, -1
	s_waitcnt lgkmcnt(4)
	v_and_b32_e32 v17, 0xff, v17
	s_mov_b64 exec, s[44:45]
	v_lshl_add_u32 v20, v17, 1, v179
	ds_write_b16 v20, v19
	s_mov_b64 exec, s[22:23]
	s_cbranch_execz .Lm6_nb10
	v_ashrrev_i32_e32 v22, 31, v98
	v_sub_u32_e32 v19, 0x1fff, v19
	v_lshl_add_u32 v20, v17, 2, v169
	v_bitop3_b32 v21, v22, v98, s64 bitop3:0x36
	v_and_or_b32 v21, v21, s65, v19
	ds_write_b32 v20, v21
.Lm6_nb10:
	s_mov_b64 exec, -1
	v_cmp_ge_f32_e64 s[44:45], v101, v122
	v_cmp_ge_f32_e64 s[22:23], v101, v123
	v_or_b32_e32 v19, 25, v124
	v_cndmask_b32_e64 v120, v171, v180, s[44:45]
	s_mov_b64 exec, s[22:23]
	ds_add_rtn_u32 v17, v120, v222
	s_andn2_b64 s[22:23], s[22:23], s[44:45]
	s_mov_b64 exec, -1
	s_waitcnt lgkmcnt(4)
	v_and_b32_e32 v23, 0xff, v23
	s_mov_b64 exec, s[20:21]
	v_lshl_add_u32 v20, v23, 1, v179
	ds_write_b16 v20, v24
	s_mov_b64 exec, s[2:3]
	s_cbranch_execz .Lm6_nb11
	v_ashrrev_i32_e32 v22, 31, v99
	v_sub_u32_e32 v24, 0x1fff, v24
	v_lshl_add_u32 v20, v23, 2, v169
	v_bitop3_b32 v21, v22, v99, s64 bitop3:0x36
	v_and_or_b32 v21, v21, s65, v24
	ds_write_b32 v20, v21
.Lm6_nb11:
	s_mov_b64 exec, -1
	v_cmp_ge_f32_e64 s[20:21], v102, v122
	v_cmp_ge_f32_e64 s[2:3], v102, v123
	v_or_b32_e32 v24, 26, v124
	v_cndmask_b32_e64 v121, v171, v180, s[20:21]
	s_mov_b64 exec, s[2:3]
	ds_add_rtn_u32 v23, v121, v222
	s_andn2_b64 s[2:3], s[2:3], s[20:21]
	s_mov_b64 exec, -1
	s_waitcnt lgkmcnt(4)
	v_and_b32_e32 v16, 0xff, v16
	s_mov_b64 exec, s[40:41]
	v_lshl_add_u32 v20, v16, 1, v179
	ds_write_b16 v20, v18
	s_mov_b64 exec, s[42:43]
	s_cbranch_execz .Lm6_nb12
	v_ashrrev_i32_e32 v22, 31, v100
	v_sub_u32_e32 v18, 0x1fff, v18
	v_lshl_add_u32 v20, v16, 2, v169
	v_bitop3_b32 v21, v22, v100, s64 bitop3:0x36
	v_and_or_b32 v21, v21, s65, v18
	ds_write_b32 v20, v21
.Lm6_nb12:
	s_mov_b64 exec, -1
	v_cmp_ge_f32_e64 s[40:41], v103, v122
	v_cmp_ge_f32_e64 s[42:43], v103, v123
	v_or_b32_e32 v18, 27, v124
	v_cndmask_b32_e64 v119, v171, v180, s[40:41]
	s_mov_b64 exec, s[42:43]
	ds_add_rtn_u32 v16, v119, v222
	s_andn2_b64 s[42:43], s[42:43], s[40:41]
	s_mov_b64 exec, -1
	s_waitcnt lgkmcnt(4)
	v_and_b32_e32 v17, 0xff, v17
	s_mov_b64 exec, s[44:45]
	v_lshl_add_u32 v20, v17, 1, v179
	ds_write_b16 v20, v19
	s_mov_b64 exec, s[22:23]
	s_cbranch_execz .Lm6_nb13
	v_ashrrev_i32_e32 v22, 31, v101
	v_sub_u32_e32 v19, 0x1fff, v19
	v_lshl_add_u32 v20, v17, 2, v169
	v_bitop3_b32 v21, v22, v101, s64 bitop3:0x36
	v_and_or_b32 v21, v21, s65, v19
	ds_write_b32 v20, v21

;     ...
;     for (int it = 0; it < nit; ++it) {
;         const int kt = kt0 + 4 * (it >> 1), kb = it & 1;
;         const int itn = it + 1 < nit ? it + 1 : it;
;         const bf16_t* np = ikp + (size_t)(256 * (itn >> 1) + 32 * (itn & 1)) * NZ; const bf16x8 n0 = *(const bf16x8*)np, n1 = *(const bf16x8*)(np + 16);
;     ...
;         a0 = n0; a1 = n1;
;     }
.Lm6_nb15:
	s_mov_b64 exec, -1
	s_waitcnt vmcnt(0)
	v_mov_b64_e32 v[132:133], v[64:65]
	v_mov_b64_e32 v[134:135], v[66:67]
	v_mov_b64_e32 v[128:129], v[68:69]
	v_mov_b64_e32 v[130:131], v[70:71]
	s_cmp_lg_u32 s25, s1
	s_mov_b32 s18, s1
	s_cbranch_scc1 .Lm6_loop
	s_nop 0
	s_nop 0
	s_nop 0
	s_nop 0
	s_nop 0
	s_nop 0
	s_nop 0
	s_nop 0
	s_nop 0
	s_nop 0
	s_nop 0
	s_nop 0
	s_nop 0
	s_nop 0
	s_nop 0
	s_nop 0
	s_nop 0
	s_nop 0
	s_nop 0
	s_nop 0
